# speedup vs baseline: 1.0011x; 1.0011x over previous
; __device__ __forceinline__ float b2f(u16 b) { return __uint_as_float(((unsigned)b) << 16); }
; __device__ __forceinline__ float sigmoidf_(float x) { return __builtin_amdgcn_rcpf(1.f + __builtin_amdgcn_exp2f(-1.4426950408889634f * x)); }
; #define MFMA16(a, b, c) __builtin_amdgcn_mfma_f32_16x16x32_bf16(a, b, c, 0, 0, 0)
; #define MFMA4(a, b, c) __builtin_amdgcn_mfma_f32_16x16x16bf16_1k(a, b, c, 0, 0, 0)
; __device__ __forceinline__ void scan_pc(const Params& p, int j, const u16* R, const u16* K, const u16* V, u16* Y, u16* YB) {
;     ...
;       f32x4 cw = {0.f, 0.f, 0.f, 0.f}, ca = {0.f, 0.f, 0.f, 0.f};
;       _Pragma("unroll") for (int ks = 0; ks < 2; ++ks) { cw = MFMA16(q_.rw[ks], LB[ks * 64], cw); ca = MFMA16(q_.ra[ks], LB[(2 + ks) * 64], ca); }
;       float kv[4], kk[4], ic[4], lw[4];
;       _Pragma("unroll") for (int jj = 0; jj < 4; ++jj) {
;         kv[jj] = b2f(q_.rk[jj]);
;         kk[jj] = kv[jj] * kkme;
;         float ss = row_sum(kk[jj] * kk[jj]);
;         reinterpret_cast<float*>(IMG + IMG_PL)[128 + w4 * 16 + fq * 4 + jj] = ss;
;         lw[jj] = -0.8750360036f * sigmoidf_(w0c + cw[jj]);
;         ic[jj] = sigmoidf_(a0c + ca[jj]);
;       }
;       s4 lhi = pack4(lw[0], lw[1], lw[2], lw[3]);
;       s4 llo = pack4(lw[0] - b2f((u16)lhi[0]), lw[1] - b2f((u16)lhi[1]), lw[2] - b2f((u16)lhi[2]), lw[3] - b2f((u16)lhi[3]));
;       f32x4 cum = {0.f, 0.f, 0.f, 0.f};
;       cum = MFMA4(ltri, lhi, cum);
;       cum = MFMA4(ltri, llo, cum);
;       float bt[4], kt[4], ep3 = 0.f;
;       _Pragma("unroll") for (int jj = 0; jj < 4; ++jj) {
;         float ep = __builtin_amdgcn_exp2f(cum[jj]), em = __builtin_amdgcn_exp2f(-cum[jj]), ex = __builtin_amdgcn_exp2f(cum[jj] - lw[jj]);
;         float at = -kk[jj] * ex;
;         float rraw = b2f(q_.rr[jj]);
;         float rt = rraw * ep;
;         float kd = kv[jj] * (1.f + (ic[jj] - 1.f) * kac);
;         bt[jj] = kk[jj] * ic[jj] * em;
;         kt[jj] = kd * em;
;         int t = fq * 4 + jj, kc = w4 * 16 + fr;
;         float bsum = row_sum(rraw * kd * rkc);
;         reinterpret_cast<float*>(IMG + IMG_PL)[64 + w4 * 16 + t] = bsum;
.LBB0_2713:
	ds_read_b128 v[32:35], v111
	s_mov_b32 s26, 0xbf60025c
	s_waitcnt lgkmcnt(0)
	v_mfma_f32_16x16x32_bf16 v[8:11], v[8:11], v[32:35], 0
	ds_read_b128 v[32:35], v111 offset:2048
	s_waitcnt vmcnt(6) lgkmcnt(0)
	v_mfma_f32_16x16x32_bf16 v[12:15], v[12:15], v[32:35], 0
	ds_read_b128 v[32:35], v111 offset:1024
	s_waitcnt lgkmcnt(0)
	v_mfma_f32_16x16x32_bf16 v[0:3], v[0:3], v[32:35], v[8:11]
	s_nop 2
	ds_read_b128 v[8:11], v111 offset:3072
	s_waitcnt vmcnt(5) lgkmcnt(0)
	v_mfma_f32_16x16x32_bf16 v[4:7], v[4:7], v[8:11], v[12:15]
	s_waitcnt vmcnt(4)
	s_nop 0
	v_add_f32_e32 v0, v152, v0
	v_add_f32_e32 v1, v152, v1
	v_mul_f32_e32 v0, 0xbfb8aa3b, v0
	s_waitcnt vmcnt(3)
	s_nop 1
	v_add_f32_e32 v4, v153, v4
	v_mul_f32_e32 v4, 0xbfb8aa3b, v4
	v_exp_f32_e32 v4, v4
	v_mul_f32_e32 v1, 0xbfb8aa3b, v1
	v_add_f32_e32 v2, v152, v2
	v_add_f32_e32 v3, v152, v3
	v_add_f32_e32 v4, 1.0, v4
	v_rcp_f32_e32 v8, v4
	v_add_f32_e32 v4, v153, v5
	v_mul_f32_e32 v4, 0xbfb8aa3b, v4
	v_exp_f32_e32 v4, v4
	v_exp_f32_e32 v0, v0
	v_exp_f32_e32 v1, v1
	v_mul_f32_e32 v2, 0xbfb8aa3b, v2
	v_add_f32_e32 v4, 1.0, v4
	v_rcp_f32_e32 v9, v4
	v_add_f32_e32 v4, v153, v6
	v_mul_f32_e32 v4, 0xbfb8aa3b, v4
	v_exp_f32_e32 v4, v4
	v_mul_f32_e32 v3, 0xbfb8aa3b, v3
	v_exp_f32_e32 v2, v2
	v_exp_f32_e32 v3, v3
	v_add_f32_e32 v4, 1.0, v4
	v_rcp_f32_e32 v6, v4
	v_add_f32_e32 v4, v153, v7
	v_add_f32_e32 v0, 1.0, v0
	v_add_f32_e32 v1, 1.0, v1
	v_mul_f32_e32 v4, 0xbfb8aa3b, v4
	v_rcp_f32_e32 v0, v0
	v_rcp_f32_e32 v1, v1
	v_add_f32_e32 v2, 1.0, v2
	v_add_f32_e32 v3, 1.0, v3
	v_exp_f32_e32 v4, v4
	v_rcp_f32_e32 v2, v2
	v_rcp_f32_e32 v3, v3
	v_pk_mul_f32 v[10:11], v[0:1], s[26:27] op_sel_hi:[1,0]
	v_add_f32_e32 v4, 1.0, v4
	v_rcp_f32_e32 v7, v4
	v_pk_mul_f32 v[12:13], v[2:3], s[26:27] op_sel_hi:[1,0]
	v_cvt_pk_bf16_f32 v4, v10, v11
	v_cvt_pk_bf16_f32 v5, v12, v13
	v_and_b32_e32 v15, 0xffff0000, v4
	v_lshlrev_b32_e32 v14, 16, v4
	v_pk_fma_f32 v[0:1], v[0:1], s[26:27], v[14:15] op_sel_hi:[1,0,1] neg_lo:[0,0,1] neg_hi:[0,0,1]
	v_and_b32_e32 v15, 0xffff0000, v5
	v_lshlrev_b32_e32 v14, 16, v5
	v_pk_fma_f32 v[2:3], v[2:3], s[26:27], v[14:15] op_sel_hi:[1,0,1] neg_lo:[0,0,1] neg_hi:[0,0,1]
	v_cvt_pk_bf16_f32 v14, v0, v1
	v_cvt_pk_bf16_f32 v15, v2, v3
	v_mfma_f32_16x16x16_bf16 v[0:3], v[72:73], v[4:5], 0
	s_nop 0
	v_mfma_f32_16x16x16_bf16 v[2:5], v[72:73], v[14:15], v[0:3]
	s_nop 7
	v_sub_f32_e32 v0, v2, v10
	v_exp_f32_e32 v34, v2
	v_exp_f32_e64 v14, -v2
	v_exp_f32_e32 v35, v0
	v_exp_f32_e32 v36, v3
	v_exp_f32_e64 v15, -v3
	v_sub_f32_e32 v0, v3, v11
	v_and_b32_e32 v3, 0xffff0000, v165
	v_lshlrev_b32_e32 v2, 16, v165
	s_waitcnt vmcnt(1)
	v_pk_mul_f32 v[32:33], v[76:77], v[2:3] op_sel_hi:[0,1]
	v_exp_f32_e32 v37, v0
	v_pk_mul_f32 v[0:1], v[32:33], v[32:33]
	s_nop 1
	v_mov_b32_dpp v0, v0 quad_perm:[1,0,3,2] row_mask:0xf bank_mask:0xf bound_ctrl:1
	v_mov_b32_dpp v1, v1 quad_perm:[1,0,3,2] row_mask:0xf bank_mask:0xf bound_ctrl:1
	v_pk_fma_f32 v[0:1], v[32:33], v[32:33], v[0:1]
	s_nop 1
	v_mov_b32_dpp v10, v0 quad_perm:[2,3,0,1] row_mask:0xf bank_mask:0xf bound_ctrl:1
	v_mov_b32_dpp v11, v1 quad_perm:[2,3,0,1] row_mask:0xf bank_mask:0xf bound_ctrl:1
	v_pk_add_f32 v[0:1], v[0:1], v[10:11]
	s_nop 1
	v_mov_b32_dpp v10, v0 row_half_mirror row_mask:0xf bank_mask:0xf bound_ctrl:1
	v_mov_b32_dpp v11, v1 row_half_mirror row_mask:0xf bank_mask:0xf bound_ctrl:1
	v_pk_add_f32 v[0:1], v[0:1], v[10:11]
	s_nop 1
	v_mov_b32_dpp v10, v0 row_ror:8 row_mask:0xf bank_mask:0xf bound_ctrl:1
	v_mov_b32_dpp v11, v1 row_ror:8 row_mask:0xf bank_mask:0xf bound_ctrl:1
	v_pk_add_f32 v[10:11], v[0:1], v[10:11]
	v_mul_f32_e64 v0, v35, -v32
	v_cvt_pk_bf16_f32 v0, v0, s0
	ds_write_b16 v118, v0 offset:17728
	v_pk_mul_f32 v[0:1], v[32:33], v[8:9]
	v_pk_add_f32 v[8:9], v[8:9], -1.0 op_sel_hi:[1,0]
	v_pk_mul_f32 v[0:1], v[0:1], v[14:15]
	v_pk_fma_f32 v[8:9], v[74:75], v[8:9], 1.0 op_sel_hi:[0,1,0]
	v_pk_mul_f32 v[8:9], v[8:9], v[2:3]
	v_cvt_pk_bf16_f32 v32, v0, s0
	v_pk_mul_f32 v[2:3], v[8:9], v[14:15]
	v_and_b32_e32 v15, 0xffff0000, v164
	v_cvt_pk_bf16_f32 v14, v2, s0
	ds_write_b16 v119, v14 offset:24640
	v_lshlrev_b32_e32 v14, 16, v164
	v_pk_mul_f32 v[8:9], v[8:9], v[14:15]
	ds_write_b16 v119, v32 offset:22336
	v_mul_f32_e32 v32, v34, v14
	v_mul_f32_e32 v34, v36, v15
	s_waitcnt vmcnt(0)
; __device__ __forceinline__ float b2f(u16 b) { return __uint_as_float(((unsigned)b) << 16); }
; __device__ __forceinline__ void scan_pc(const Params& p, int j, const u16* R, const u16* K, const u16* V, u16* Y, u16* YB) {
;     ...
;     auto load_raw = [&](int c, Raw& q_) {
;       unsigned offA = (unsigned)(offA0 + c * dA);
;       _Pragma("unroll") for (int ks = 0; ks < 2; ++ks) { q_.rw[ks] = ldo<bf16x8>(wmid, offA + ks * 64); q_.ra[ks] = ldo<bf16x8>(amid, offA + ks * 64); }
;       _Pragma("unroll") for (int jj = 0; jj < 4; ++jj) {
;         unsigned off = (unsigned)(offK0[jj] + c * dK);
;         q_.rk[jj] = ldo<u16>(K, off); q_.rr[jj] = ldo<u16>(R, off); q_.rv[jj] = ldo<u16>(V, off);
;       }
;     };
;     ...
;       _Pragma("unroll") for (int jj = 0; jj < 4; ++jj) {
;         float ep = __builtin_amdgcn_exp2f(cum[jj]), em = __builtin_amdgcn_exp2f(-cum[jj]), ex = __builtin_amdgcn_exp2f(cum[jj] - lw[jj]);
;         float at = -kk[jj] * ex;
;         float rraw = b2f(q_.rr[jj]);
;         float rt = rraw * ep;
;         float kd = kv[jj] * (1.f + (ic[jj] - 1.f) * kac);
;         bt[jj] = kk[jj] * ic[jj] * em;
;         kt[jj] = kd * em;
;         int t = fq * 4 + jj, kc = w4 * 16 + fr;
;         float bsum = row_sum(rraw * kd * rkc);
;         reinterpret_cast<float*>(IMG + IMG_PL)[64 + w4 * 16 + t] = bsum;
;         IMG[(0 * 16 + t) * XT_LD + kc] = f2b(at);
;         IMG[(1 * 16 + t) * XT_LD + kc] = f2b(rt);
;         IMG[(2 * 16 + t) * XT_LD + kc] = f2b(bt[jj]);
;         IMG[(3 * 16 + t) * XT_LD + kc] = f2b(kt[jj]);
;         if (jj == 3) ep3 = ep;
;       }
;       if (fq == 3) reinterpret_cast<float*>(IMG + IMG_PL)[w4 * 16 + fr] = ep3;
;       *reinterpret_cast<s4*>(IMG + IMG_XK + (0 * 64 + w4 * 16 + fr) * XK_LD + fq * 4) = pack4(bt[0], bt[1], bt[2], bt[3]);
;       *reinterpret_cast<s4*>(IMG + IMG_XK + (1 * 64 + w4 * 16 + fr) * XK_LD + fq * 4) = pack4(kt[0], kt[1], kt[2], kt[3]);
;       s4 vp; _Pragma("unroll") for (int jj = 0; jj < 4; ++jj) vp[jj] = (short)q_.rv[jj];
;       *reinterpret_cast<s4*>(IMG + IMG_VT + (w4 * 16 + fr) * XK_LD + fq * 4) = vp;
;     };
	v_pk_mul_f32 v[14:15], v[78:79], v[8:9] op_sel_hi:[0,1]
	v_mul_f32_e64 v35, v37, -v33
	v_cvt_pk_bf16_f32 v32, v32, s0
	v_mov_b32_dpp v14, v14 quad_perm:[1,0,3,2] row_mask:0xf bank_mask:0xf bound_ctrl:1
	v_mov_b32_dpp v15, v15 quad_perm:[1,0,3,2] row_mask:0xf bank_mask:0xf bound_ctrl:1
	v_pk_fma_f32 v[8:9], v[78:79], v[8:9], v[14:15] op_sel_hi:[0,1,1]
	ds_write_b16 v119, v32 offset:20032
	s_nop 0
	v_mov_b32_dpp v14, v8 quad_perm:[2,3,0,1] row_mask:0xf bank_mask:0xf bound_ctrl:1
	v_mov_b32_dpp v15, v9 quad_perm:[2,3,0,1] row_mask:0xf bank_mask:0xf bound_ctrl:1
	v_pk_add_f32 v[8:9], v[8:9], v[14:15]
	s_nop 1
	v_mov_b32_dpp v14, v8 row_half_mirror row_mask:0xf bank_mask:0xf bound_ctrl:1
	v_mov_b32_dpp v15, v9 row_half_mirror row_mask:0xf bank_mask:0xf bound_ctrl:1
	v_pk_add_f32 v[8:9], v[8:9], v[14:15]
	s_nop 1
	v_mov_b32_dpp v14, v8 row_ror:8 row_mask:0xf bank_mask:0xf bound_ctrl:1
	v_mov_b32_dpp v15, v9 row_ror:8 row_mask:0xf bank_mask:0xf bound_ctrl:1
	v_pk_add_f32 v[32:33], v[8:9], v[14:15]
	v_cvt_pk_bf16_f32 v8, v35, s0
	ds_write_b16 v121, v8 offset:17728
	v_cvt_pk_bf16_f32 v8, v34, s0
	ds_write_b16 v122, v8 offset:20032
	v_cvt_pk_bf16_f32 v8, v1, s0
	v_exp_f32_e32 v9, v4
	v_exp_f32_e64 v14, -v4
	v_sub_f32_e32 v4, v4, v12
	v_and_b32_e32 v35, 0xffff0000, v163
	v_lshlrev_b32_e32 v34, 16, v163
	ds_write_b16 v122, v8 offset:22336
	v_cvt_pk_bf16_f32 v8, v3, s0
	v_exp_f32_e32 v38, v4
	v_sub_f32_e32 v4, v5, v13
	v_pk_mul_f32 v[36:37], v[76:77], v[34:35] op_sel_hi:[0,1]
	ds_write_b16 v122, v8 offset:24640
	v_exp_f32_e32 v8, v5
	v_exp_f32_e64 v15, -v5
	v_exp_f32_e32 v39, v4
	v_pk_mul_f32 v[4:5], v[36:37], v[36:37]
	s_nop 1
	v_mov_b32_dpp v4, v4 quad_perm:[1,0,3,2] row_mask:0xf bank_mask:0xf bound_ctrl:1
	v_mov_b32_dpp v5, v5 quad_perm:[1,0,3,2] row_mask:0xf bank_mask:0xf bound_ctrl:1
	v_pk_fma_f32 v[4:5], v[36:37], v[36:37], v[4:5]
	s_nop 1
	v_mov_b32_dpp v12, v4 quad_perm:[2,3,0,1] row_mask:0xf bank_mask:0xf bound_ctrl:1
	v_mov_b32_dpp v13, v5 quad_perm:[2,3,0,1] row_mask:0xf bank_mask:0xf bound_ctrl:1
	v_pk_add_f32 v[4:5], v[4:5], v[12:13]
	s_nop 1
	v_mov_b32_dpp v12, v4 row_half_mirror row_mask:0xf bank_mask:0xf bound_ctrl:1
	v_mov_b32_dpp v13, v5 row_half_mirror row_mask:0xf bank_mask:0xf bound_ctrl:1
	v_pk_add_f32 v[4:5], v[4:5], v[12:13]
	s_nop 1
	v_mov_b32_dpp v12, v4 row_ror:8 row_mask:0xf bank_mask:0xf bound_ctrl:1
	v_mov_b32_dpp v13, v5 row_ror:8 row_mask:0xf bank_mask:0xf bound_ctrl:1
	v_pk_add_f32 v[12:13], v[4:5], v[12:13]
	v_mul_f32_e64 v4, v38, -v36
	v_cvt_pk_bf16_f32 v4, v4, s0
	ds_write_b16 v123, v4 offset:17728
	v_pk_mul_f32 v[4:5], v[36:37], v[6:7]
	v_pk_add_f32 v[6:7], v[6:7], -1.0 op_sel_hi:[1,0]
	v_pk_mul_f32 v[4:5], v[4:5], v[14:15]
	ds_write_b128 v116, v[10:13] offset:35136
	v_cvt_pk_bf16_f32 v10, v4, s0
	v_pk_fma_f32 v[6:7], v[74:75], v[6:7], 1.0 op_sel_hi:[0,1,0]
	ds_write_b16 v124, v10 offset:22336
	v_pk_mul_f32 v[10:11], v[6:7], v[34:35]
	v_and_b32_e32 v13, 0xffff0000, v162
	v_pk_mul_f32 v[6:7], v[10:11], v[14:15]
	v_mul_f32_e64 v36, v39, -v37
	v_cvt_pk_bf16_f32 v12, v6, s0
	ds_write_b16 v124, v12 offset:24640
	v_lshlrev_b32_e32 v12, 16, v162
	v_mul_f32_e32 v9, v9, v12
	v_cvt_pk_bf16_f32 v9, v9, s0
	v_pk_mul_f32 v[10:11], v[10:11], v[12:13]
	ds_write_b16 v124, v9 offset:20032
	v_mul_f32_e32 v9, v8, v13
	v_pk_mul_f32 v[12:13], v[78:79], v[10:11] op_sel_hi:[0,1]
	v_cvt_pk_bf16_f32 v9, v9, s0
	ds_write_b16 v126, v9 offset:20032
	v_mov_b32_dpp v12, v12 quad_perm:[1,0,3,2] row_mask:0xf bank_mask:0xf bound_ctrl:1
	v_mov_b32_dpp v13, v13 quad_perm:[1,0,3,2] row_mask:0xf bank_mask:0xf bound_ctrl:1
	v_pk_fma_f32 v[10:11], v[78:79], v[10:11], v[12:13] op_sel_hi:[0,1,1]
	v_cvt_pk_bf16_f32 v9, v5, s0
	ds_write_b16 v126, v9 offset:22336
	v_mov_b32_dpp v12, v10 quad_perm:[2,3,0,1] row_mask:0xf bank_mask:0xf bound_ctrl:1
	v_mov_b32_dpp v13, v11 quad_perm:[2,3,0,1] row_mask:0xf bank_mask:0xf bound_ctrl:1
	v_pk_add_f32 v[10:11], v[10:11], v[12:13]
	v_cvt_pk_bf16_f32 v9, v7, s0
	ds_write_b16 v126, v9 offset:24640
	v_mov_b32_dpp v12, v10 row_half_mirror row_mask:0xf bank_mask:0xf bound_ctrl:1
	v_mov_b32_dpp v13, v11 row_half_mirror row_mask:0xf bank_mask:0xf bound_ctrl:1
	v_pk_add_f32 v[10:11], v[10:11], v[12:13]
	s_nop 1
	v_mov_b32_dpp v12, v10 row_ror:8 row_mask:0xf bank_mask:0xf bound_ctrl:1
	v_mov_b32_dpp v13, v11 row_ror:8 row_mask:0xf bank_mask:0xf bound_ctrl:1
	v_pk_add_f32 v[34:35], v[10:11], v[12:13]
	v_cvt_pk_bf16_f32 v10, v36, s0
	ds_write_b128 v116, v[32:35] offset:34880
	ds_write_b16 v125, v10 offset:17728
	s_and_saveexec_b64 s[26:27], s[12:13]
	v_add_u32_e32 v9, v110, v113
	ds_write_b32 v9, v8 offset:34624
	s_or_b64 exec, exec, s[26:27]
	v_cvt_pk_bf16_f32 v0, v0, v1
	v_cvt_pk_bf16_f32 v1, v4, v5
	v_add_u32_e32 v4, v132, v133
	v_cvt_pk_bf16_f32 v2, v2, v3
	v_cvt_pk_bf16_f32 v3, v6, v7
	v_add_u32_e32 v5, 0x140, v4
	s_mul_i32 s3, s31, 0x1800
	ds_write2st64_b64 v5, v[0:1], v[2:3] offset0:52 offset1:57
	ds_write_b64 v4, v[84:85] offset:32064
	v_add_u32_e32 v4, s3, v80
	s_mul_i32 s3, s31, 0x18000
	global_load_dwordx4 v[8:11], v4, s[72:73]
	global_load_dwordx4 v[12:15], v4, s[60:61]
	global_load_dwordx4 v[0:3], v4, s[72:73] offset:64
	s_nop 0
	global_load_dwordx4 v[4:7], v4, s[60:61] offset:64
	v_add_u32_e32 v32, s3, v154
	v_add_u32_e32 v35, s3, v155
	v_add_u32_e32 v38, s3, v156
	v_add_u32_e32 v41, s3, v157
	global_load_ushort v218, v32, s[58:59]
	global_load_ushort v222, v32, s[54:55]
	s_nop 0
	global_load_ushort v226, v32, s[4:5]
	s_nop 0
	global_load_ushort v219, v35, s[58:59]
	global_load_ushort v223, v35, s[54:55]
	s_nop 0
	global_load_ushort v227, v35, s[4:5]
	s_nop 0
	global_load_ushort v220, v38, s[58:59]
	global_load_ushort v224, v38, s[54:55]
	s_nop 0
	global_load_ushort v228, v38, s[4:5]
	s_nop 0
	global_load_ushort v221, v41, s[58:59]
	global_load_ushort v225, v41, s[54:55]
	s_nop 0
	global_load_ushort v229, v41, s[4:5]
	s_mov_b32 s3, 0x5040100
	v_mov_b32_e32 v128, v129
	v_mov_b64_e32 v[86:87], v[128:129]
	v_mov_b64_e32 v[88:89], v[128:129]
	s_waitcnt vmcnt(8)
	v_perm_b32 v165, v219, v218, s3
	s_waitcnt vmcnt(7)
	v_perm_b32 v164, v223, v222, s3
	s_waitcnt vmcnt(2)
	v_perm_b32 v163, v221, v220, s3
	s_waitcnt vmcnt(1)
	v_perm_b32 v162, v225, v224, s3
	v_perm_b32 v84, v227, v226, s3
	s_waitcnt vmcnt(0)
	v_perm_b32 v85, v229, v228, s3
	ds_read_b128 v[230:233], v111
	ds_read_b128 v[234:237], v111 offset:2048
	ds_read_b128 v[238:241], v111 offset:1024
	ds_read_b128 v[242:245], v111 offset:3072

; __device__ __forceinline__ float b2f(u16 b) { return __uint_as_float(((unsigned)b) << 16); }
; __device__ __forceinline__ float sigmoidf_(float x) { return __builtin_amdgcn_rcpf(1.f + __builtin_amdgcn_exp2f(-1.4426950408889634f * x)); }
; __device__ __forceinline__ void scan_pc(const Params& p, int j, const u16* R, const u16* K, const u16* V, u16* Y, u16* YB) {
;     ...
;     auto load_raw = [&](int c, Raw& q_) {
;       unsigned offA = (unsigned)(offA0 + c * dA);
;       _Pragma("unroll") for (int ks = 0; ks < 2; ++ks) { q_.rw[ks] = ldo<bf16x8>(wmid, offA + ks * 64); q_.ra[ks] = ldo<bf16x8>(amid, offA + ks * 64); }
;       _Pragma("unroll") for (int jj = 0; jj < 4; ++jj) {
;         unsigned off = (unsigned)(offK0[jj] + c * dK);
;         q_.rk[jj] = ldo<u16>(K, off); q_.rr[jj] = ldo<u16>(R, off); q_.rv[jj] = ldo<u16>(V, off);
;       }
;     };
;     auto load_yold = [&](int c) {
;       _Pragma("unroll") for (int jj = 0; jj < 4; ++jj) yo[jj] = b2f(ldo<u16>(Yw, (unsigned)(offK0[jj] + c * dK)));
;     };
;     auto stage_a = [&](int c, const Raw& q_) {
;       u16* IMG = shm + (c % 3) * IMG_ELEMS;
;       f32x4 cw = {0.f, 0.f, 0.f, 0.f}, ca = {0.f, 0.f, 0.f, 0.f};
;       _Pragma("unroll") for (int ks = 0; ks < 2; ++ks) { cw = MFMA16(q_.rw[ks], LB[ks * 64], cw); ca = MFMA16(q_.ra[ks], LB[(2 + ks) * 64], ca); }
;       float kv[4], kk[4], ic[4], lw[4];
;       _Pragma("unroll") for (int jj = 0; jj < 4; ++jj) {
;         kv[jj] = b2f(q_.rk[jj]);
;         kk[jj] = kv[jj] * kkme;
;         float ss = row_sum(kk[jj] * kk[jj]);
;         reinterpret_cast<float*>(IMG + IMG_PL)[128 + w4 * 16 + fq * 4 + jj] = ss;
;         lw[jj] = -0.8750360036f * sigmoidf_(w0c + cw[jj]);
;         ic[jj] = sigmoidf_(a0c + ca[jj]);
;       }
;       s4 lhi = pack4(lw[0], lw[1], lw[2], lw[3]);
;       s4 llo = pack4(lw[0] - b2f((u16)lhi[0]), lw[1] - b2f((u16)lhi[1]), lw[2] - b2f((u16)lhi[2]), lw[3] - b2f((u16)lhi[3]));
;       f32x4 cum = {0.f, 0.f, 0.f, 0.f};
;       cum = MFMA4(ltri, lhi, cum);
;       cum = MFMA4(ltri, llo, cum);
;       float bt[4], kt[4], ep3 = 0.f;
;       _Pragma("unroll") for (int jj = 0; jj < 4; ++jj) {
;         float ep = __builtin_amdgcn_exp2f(cum[jj]), em = __builtin_amdgcn_exp2f(-cum[jj]), ex = __builtin_amdgcn_exp2f(cum[jj] - lw[jj]);
;     ...
;         if (c + 2 < nch) stage_a(c + 2, rn);
;         load_raw(min(c + 4, nch - 1), rn);
.LBB0_2739:
	s_or_saveexec_b64 s[26:27], s[26:27]
	s_mul_hi_u32 s30, s3, 0xaaaaaaab
	s_lshr_b32 s30, s30, 1
	s_mul_i32 s30, s30, 3
	s_sub_i32 s76, 2, s30
	v_add_u32_e32 v94, 2, v90
	s_xor_b64 exec, exec, s[26:27]
	s_cbranch_execz .LBB0_2745
	s_waitcnt vmcnt(16)
	v_lshl_or_b32 v161, v207, 16, v206
	v_lshl_or_b32 v159, v209, 16, v208
	v_lshl_or_b32 v160, v211, 16, v210
	v_lshl_or_b32 v158, v213, 16, v212
	v_lshl_or_b32 v82, v215, 16, v214
	v_lshl_or_b32 v83, v217, 16, v216
	v_add_u32_e32 v50, 4, v90
	v_min_i32_e32 v50, s29, v50
	v_mul_lo_u32 v50, v50, s8
	v_add_u32_e32 v51, v50, v154
	v_add_u32_e32 v54, v50, v155
	v_add_u32_e32 v55, v50, v156
	v_add_u32_e32 v50, v50, v157
	global_load_ushort v208, v55, s[58:59]
	global_load_ushort v209, v50, s[58:59]
	global_load_ushort v206, v51, s[58:59]
	global_load_ushort v210, v51, s[54:55]
	global_load_ushort v207, v54, s[58:59]
	global_load_ushort v211, v54, s[54:55]
	global_load_ushort v212, v55, s[54:55]
	global_load_ushort v216, v55, s[4:5]
	global_load_ushort v215, v54, s[4:5]
	global_load_ushort v214, v51, s[4:5]
	global_load_ushort v213, v50, s[54:55]
	global_load_ushort v217, v50, s[4:5]
	v_add_u32_e32 v50, 2, v90
	v_cmp_gt_u32_e32 vcc, s2, v50
	s_and_saveexec_b64 s[30:31], vcc
	s_cbranch_execz .LBB0_2744
	s_mov_b32 s62, 0xbf60025c
	v_add_u32_e32 v50, s76, v90
	s_waitcnt lgkmcnt(3)
	v_mfma_f32_16x16x32_bf16 v[20:23], v[20:23], v[230:233], 0
	s_waitcnt lgkmcnt(2)
	v_mfma_f32_16x16x32_bf16 v[28:31], v[28:31], v[234:237], 0
	s_waitcnt lgkmcnt(1)
	v_mfma_f32_16x16x32_bf16 v[16:19], v[16:19], v[238:241], v[20:23]
	s_waitcnt lgkmcnt(0)
	v_mfma_f32_16x16x32_bf16 v[20:23], v[24:27], v[242:245], v[28:31]
	s_nop 5
	v_add_f32_e32 v16, v152, v16
	v_add_f32_e32 v17, v152, v17
	v_mul_f32_e32 v16, 0xbfb8aa3b, v16
	s_nop 2
	v_add_f32_e32 v20, v153, v20
	v_mul_f32_e32 v20, 0xbfb8aa3b, v20
	v_exp_f32_e32 v20, v20
	v_mul_f32_e32 v17, 0xbfb8aa3b, v17
	v_add_f32_e32 v18, v152, v18
	v_add_f32_e32 v19, v152, v19
	v_add_f32_e32 v20, 1.0, v20
	v_rcp_f32_e32 v26, v20
	v_add_f32_e32 v20, v153, v21
	v_mul_f32_e32 v20, 0xbfb8aa3b, v20
	v_exp_f32_e32 v20, v20
	v_exp_f32_e32 v16, v16
	v_exp_f32_e32 v17, v17
	v_mul_f32_e32 v18, 0xbfb8aa3b, v18
	v_add_f32_e32 v20, 1.0, v20
	v_rcp_f32_e32 v27, v20
	v_add_f32_e32 v20, v153, v22
	v_mul_f32_e32 v20, 0xbfb8aa3b, v20
	v_exp_f32_e32 v20, v20
	v_mul_f32_e32 v19, 0xbfb8aa3b, v19
	v_exp_f32_e32 v18, v18
	v_exp_f32_e32 v19, v19
	v_add_f32_e32 v20, 1.0, v20
	v_rcp_f32_e32 v22, v20
	v_add_f32_e32 v20, v153, v23
	v_add_f32_e32 v16, 1.0, v16
	v_add_f32_e32 v17, 1.0, v17
	v_mul_f32_e32 v20, 0xbfb8aa3b, v20
	v_rcp_f32_e32 v16, v16
	v_rcp_f32_e32 v17, v17
	v_add_f32_e32 v18, 1.0, v18
	v_add_f32_e32 v19, 1.0, v19
	v_exp_f32_e32 v20, v20
	v_rcp_f32_e32 v18, v18
	v_rcp_f32_e32 v19, v19
	v_pk_mul_f32 v[28:29], v[16:17], s[62:63] op_sel_hi:[1,0]
	v_add_f32_e32 v20, 1.0, v20
	v_rcp_f32_e32 v23, v20
	v_pk_mul_f32 v[30:31], v[18:19], s[62:63] op_sel_hi:[1,0]
	v_cvt_pk_bf16_f32 v20, v28, v29
	v_mad_u32_u24 v24, v50, s80, 0
	v_cvt_pk_bf16_f32 v21, v30, v31
	v_and_b32_e32 v51, 0xffff0000, v20
	v_lshlrev_b32_e32 v50, 16, v20
	v_pk_fma_f32 v[16:17], v[16:17], s[62:63], v[50:51] op_sel_hi:[1,0,1] neg_lo:[0,0,1] neg_hi:[0,0,1]
	v_and_b32_e32 v51, 0xffff0000, v21
	v_lshlrev_b32_e32 v50, 16, v21
	v_pk_fma_f32 v[18:19], v[18:19], s[62:63], v[50:51] op_sel_hi:[1,0,1] neg_lo:[0,0,1] neg_hi:[0,0,1]
	v_cvt_pk_bf16_f32 v50, v16, v17
	v_cvt_pk_bf16_f32 v51, v18, v19
	v_mfma_f32_16x16x16_bf16 v[16:19], v[72:73], v[20:21], 0
	v_add_u32_e32 v60, v24, v115
	v_add_u32_e32 v61, v60, v117
	v_add3_u32 v66, v24, v117, v115
	v_mfma_f32_16x16x16_bf16 v[18:21], v[72:73], v[50:51], v[16:19]
	v_add_u32_e32 v25, v24, v113
	v_add_u32_e32 v62, v25, v112
	v_lshl_add_u32 v63, v97, 2, v25
	s_nop 4
	v_sub_f32_e32 v16, v18, v28
	v_exp_f32_e32 v58, v18
	v_exp_f32_e64 v50, -v18
	v_exp_f32_e32 v59, v16
	v_exp_f32_e32 v67, v19
	v_exp_f32_e64 v51, -v19
	v_sub_f32_e32 v16, v19, v29
	v_and_b32_e32 v19, 0xffff0000, v161
	v_lshlrev_b32_e32 v18, 16, v161
	v_pk_mul_f32 v[54:55], v[76:77], v[18:19]
	v_exp_f32_e32 v68, v16
	v_pk_mul_f32 v[16:17], v[54:55], v[54:55]
	s_nop 1
	v_mov_b32_dpp v16, v16 quad_perm:[1,0,3,2] row_mask:0xf bank_mask:0xf bound_ctrl:1
	v_mov_b32_dpp v17, v17 quad_perm:[1,0,3,2] row_mask:0xf bank_mask:0xf bound_ctrl:1
	v_pk_fma_f32 v[16:17], v[54:55], v[54:55], v[16:17]
	s_nop 1
	v_mov_b32_dpp v28, v16 quad_perm:[2,3,0,1] row_mask:0xf bank_mask:0xf bound_ctrl:1
	v_mov_b32_dpp v29, v17 quad_perm:[2,3,0,1] row_mask:0xf bank_mask:0xf bound_ctrl:1
	v_pk_add_f32 v[16:17], v[16:17], v[28:29]
	s_nop 1
	v_mov_b32_dpp v28, v16 row_half_mirror row_mask:0xf bank_mask:0xf bound_ctrl:1
	v_mov_b32_dpp v29, v17 row_half_mirror row_mask:0xf bank_mask:0xf bound_ctrl:1
	v_pk_add_f32 v[16:17], v[16:17], v[28:29]
	s_nop 1
	v_mov_b32_dpp v28, v16 row_ror:8 row_mask:0xf bank_mask:0xf bound_ctrl:1
	v_mov_b32_dpp v29, v17 row_ror:8 row_mask:0xf bank_mask:0xf bound_ctrl:1
	v_pk_add_f32 v[28:29], v[16:17], v[28:29]
	v_mul_f32_e64 v16, v59, -v54
	v_cvt_pk_bf16_f32 v16, v16, s0
	ds_write_b16 v61, v16
	v_pk_mul_f32 v[16:17], v[54:55], v[26:27]
	v_pk_add_f32 v[26:27], v[26:27], -1.0 op_sel_hi:[1,0]
	v_pk_mul_f32 v[16:17], v[16:17], v[50:51]
	v_pk_fma_f32 v[26:27], v[74:75], v[26:27], 1.0 op_sel_hi:[1,1,0]
	v_cvt_pk_bf16_f32 v54, v16, s0
	v_pk_mul_f32 v[26:27], v[26:27], v[18:19]
; __device__ __forceinline__ float b2f(u16 b) { return __uint_as_float(((unsigned)b) << 16); }
; __device__ __forceinline__ void scan_pc(const Params& p, int j, const u16* R, const u16* K, const u16* V, u16* Y, u16* YB) {
;     ...
;       _Pragma("unroll") for (int jj = 0; jj < 4; ++jj) {
;         float ep = __builtin_amdgcn_exp2f(cum[jj]), em = __builtin_amdgcn_exp2f(-cum[jj]), ex = __builtin_amdgcn_exp2f(cum[jj] - lw[jj]);
;         float at = -kk[jj] * ex;
;         float rraw = b2f(q_.rr[jj]);
;         float rt = rraw * ep;
;         float kd = kv[jj] * (1.f + (ic[jj] - 1.f) * kac);
;         bt[jj] = kk[jj] * ic[jj] * em;
;         kt[jj] = kd * em;
;         int t = fq * 4 + jj, kc = w4 * 16 + fr;
;         float bsum = row_sum(rraw * kd * rkc);
;         reinterpret_cast<float*>(IMG + IMG_PL)[64 + w4 * 16 + t] = bsum;
;         IMG[(0 * 16 + t) * XT_LD + kc] = f2b(at);
;         IMG[(1 * 16 + t) * XT_LD + kc] = f2b(rt);
;         IMG[(2 * 16 + t) * XT_LD + kc] = f2b(bt[jj]);
;         IMG[(3 * 16 + t) * XT_LD + kc] = f2b(kt[jj]);
;         if (jj == 3) ep3 = ep;
;       }
;       if (fq == 3) reinterpret_cast<float*>(IMG + IMG_PL)[w4 * 16 + fr] = ep3;
;       *reinterpret_cast<s4*>(IMG + IMG_XK + (0 * 64 + w4 * 16 + fr) * XK_LD + fq * 4) = pack4(bt[0], bt[1], bt[2], bt[3]);
;       *reinterpret_cast<s4*>(IMG + IMG_XK + (1 * 64 + w4 * 16 + fr) * XK_LD + fq * 4) = pack4(kt[0], kt[1], kt[2], kt[3]);
;       s4 vp; _Pragma("unroll") for (int jj = 0; jj < 4; ++jj) vp[jj] = (short)q_.rv[jj];
;       *reinterpret_cast<s4*>(IMG + IMG_VT + (w4 * 16 + fr) * XK_LD + fq * 4) = vp;
;     };
	ds_write_b16 v66, v54 offset:4608
	v_pk_mul_f32 v[18:19], v[26:27], v[50:51]
	v_mul_f32_e64 v54, v68, -v55
	v_cvt_pk_bf16_f32 v50, v18, s0
	ds_write_b16 v66, v50 offset:6912
	v_lshlrev_b32_e32 v50, 16, v160
	v_and_b32_e32 v51, 0xffff0000, v160
	v_mul_f32_e32 v55, v58, v50
	v_cvt_pk_bf16_f32 v55, v55, s0
	v_pk_mul_f32 v[26:27], v[26:27], v[50:51]
	ds_write_b16 v66, v55 offset:2304
	v_mul_f32_e32 v55, v67, v51
	v_pk_mul_f32 v[50:51], v[78:79], v[26:27]
	v_exp_f32_e32 v66, v20
	s_nop 0
	v_mov_b32_dpp v50, v50 quad_perm:[1,0,3,2] row_mask:0xf bank_mask:0xf bound_ctrl:1
	v_mov_b32_dpp v51, v51 quad_perm:[1,0,3,2] row_mask:0xf bank_mask:0xf bound_ctrl:1
	v_pk_fma_f32 v[26:27], v[78:79], v[26:27], v[50:51]
	s_nop 1
	v_mov_b32_dpp v50, v26 quad_perm:[2,3,0,1] row_mask:0xf bank_mask:0xf bound_ctrl:1
	v_mov_b32_dpp v51, v27 quad_perm:[2,3,0,1] row_mask:0xf bank_mask:0xf bound_ctrl:1
	v_pk_add_f32 v[26:27], v[26:27], v[50:51]
	s_nop 1
	v_mov_b32_dpp v50, v26 row_half_mirror row_mask:0xf bank_mask:0xf bound_ctrl:1
	v_mov_b32_dpp v51, v27 row_half_mirror row_mask:0xf bank_mask:0xf bound_ctrl:1
	v_pk_add_f32 v[26:27], v[26:27], v[50:51]
	s_nop 1
	v_mov_b32_dpp v50, v26 row_ror:8 row_mask:0xf bank_mask:0xf bound_ctrl:1
	v_mov_b32_dpp v51, v27 row_ror:8 row_mask:0xf bank_mask:0xf bound_ctrl:1
	v_pk_add_f32 v[58:59], v[26:27], v[50:51]
	v_cvt_pk_bf16_f32 v26, v54, s0
	v_add_u32_e32 v27, v60, v120
	ds_write_b16 v27, v26
	v_cvt_pk_bf16_f32 v26, v55, s0
	v_add3_u32 v27, v24, v120, v115
	ds_write_b16 v27, v26 offset:2304
	v_cvt_pk_bf16_f32 v26, v17, s0
	v_exp_f32_e64 v50, -v20
	v_sub_f32_e32 v20, v20, v30
	v_and_b32_e32 v55, 0xffff0000, v159
	v_lshlrev_b32_e32 v54, 16, v159
	ds_write_b16 v27, v26 offset:4608
	v_cvt_pk_bf16_f32 v26, v19, s0
	v_exp_f32_e32 v67, v20
	v_sub_f32_e32 v20, v21, v31
	v_pk_mul_f32 v[60:61], v[76:77], v[54:55]
	ds_write_b16 v27, v26 offset:6912
	v_exp_f32_e32 v26, v21
	v_exp_f32_e64 v51, -v21
	v_exp_f32_e32 v68, v20
	v_pk_mul_f32 v[20:21], v[60:61], v[60:61]
	s_nop 1
	v_mov_b32_dpp v20, v20 quad_perm:[1,0,3,2] row_mask:0xf bank_mask:0xf bound_ctrl:1
	v_mov_b32_dpp v21, v21 quad_perm:[1,0,3,2] row_mask:0xf bank_mask:0xf bound_ctrl:1
	v_pk_fma_f32 v[20:21], v[60:61], v[60:61], v[20:21]
	s_nop 1
	v_mov_b32_dpp v30, v20 quad_perm:[2,3,0,1] row_mask:0xf bank_mask:0xf bound_ctrl:1
	v_mov_b32_dpp v31, v21 quad_perm:[2,3,0,1] row_mask:0xf bank_mask:0xf bound_ctrl:1
	v_pk_add_f32 v[20:21], v[20:21], v[30:31]
	s_nop 1
	v_mov_b32_dpp v30, v20 row_half_mirror row_mask:0xf bank_mask:0xf bound_ctrl:1
	v_mov_b32_dpp v31, v21 row_half_mirror row_mask:0xf bank_mask:0xf bound_ctrl:1
	v_pk_add_f32 v[20:21], v[20:21], v[30:31]
	s_nop 1
	v_mov_b32_dpp v30, v20 row_ror:8 row_mask:0xf bank_mask:0xf bound_ctrl:1
	v_mov_b32_dpp v31, v21 row_ror:8 row_mask:0xf bank_mask:0xf bound_ctrl:1
	v_pk_add_f32 v[30:31], v[20:21], v[30:31]
	v_mul_f32_e64 v20, v67, -v60
	v_cvt_pk_bf16_f32 v20, v20, s0
	ds_write_b16 v27, v20 offset:144
	v_pk_mul_f32 v[20:21], v[60:61], v[22:23]
	v_pk_add_f32 v[22:23], v[22:23], -1.0 op_sel_hi:[1,0]
	v_pk_mul_f32 v[20:21], v[20:21], v[50:51]
	ds_write_b128 v62, v[28:31] offset:17408
	v_cvt_pk_bf16_f32 v28, v20, s0
	v_pk_fma_f32 v[22:23], v[74:75], v[22:23], 1.0 op_sel_hi:[1,1,0]
	ds_write_b16 v27, v28 offset:4752
	v_pk_mul_f32 v[28:29], v[22:23], v[54:55]
	v_and_b32_e32 v31, 0xffff0000, v158
	v_pk_mul_f32 v[22:23], v[28:29], v[50:51]
	v_mul_f32_e64 v62, v68, -v61
	v_cvt_pk_bf16_f32 v30, v22, s0
	ds_write_b16 v27, v30 offset:7056
	v_lshlrev_b32_e32 v30, 16, v158
	v_mul_f32_e32 v50, v66, v30
	v_cvt_pk_bf16_f32 v50, v50, s0
	v_pk_mul_f32 v[28:29], v[28:29], v[30:31]
	ds_write_b16 v27, v50 offset:2448
	v_mul_f32_e32 v50, v26, v31
	v_pk_mul_f32 v[30:31], v[78:79], v[28:29]
	s_nop 1
	v_mov_b32_dpp v30, v30 quad_perm:[1,0,3,2] row_mask:0xf bank_mask:0xf bound_ctrl:1
	v_mov_b32_dpp v31, v31 quad_perm:[1,0,3,2] row_mask:0xf bank_mask:0xf bound_ctrl:1
	v_pk_fma_f32 v[28:29], v[78:79], v[28:29], v[30:31]
	s_nop 1
	v_mov_b32_dpp v30, v28 quad_perm:[2,3,0,1] row_mask:0xf bank_mask:0xf bound_ctrl:1
	v_mov_b32_dpp v31, v29 quad_perm:[2,3,0,1] row_mask:0xf bank_mask:0xf bound_ctrl:1
	v_pk_add_f32 v[28:29], v[28:29], v[30:31]
	s_nop 1
	v_mov_b32_dpp v30, v28 row_half_mirror row_mask:0xf bank_mask:0xf bound_ctrl:1
	v_mov_b32_dpp v31, v29 row_half_mirror row_mask:0xf bank_mask:0xf bound_ctrl:1
	v_pk_add_f32 v[28:29], v[28:29], v[30:31]
	s_nop 1
	v_mov_b32_dpp v30, v28 row_ror:8 row_mask:0xf bank_mask:0xf bound_ctrl:1
	v_mov_b32_dpp v31, v29 row_ror:8 row_mask:0xf bank_mask:0xf bound_ctrl:1
	v_pk_add_f32 v[60:61], v[28:29], v[30:31]
	v_cvt_pk_bf16_f32 v28, v62, s0
	ds_write_b16 v27, v28 offset:288
	v_cvt_pk_bf16_f32 v28, v50, s0
	ds_write_b16 v27, v28 offset:2592
	v_cvt_pk_bf16_f32 v28, v21, s0
	ds_write_b16 v27, v28 offset:4896
	v_cvt_pk_bf16_f32 v28, v23, s0
	ds_write_b128 v63, v[58:61] offset:17152
	ds_write_b16 v27, v28 offset:7200
	s_and_saveexec_b64 s[62:63], s[12:13]
	v_lshl_add_u32 v25, v96, 2, v25
	ds_write_b32 v25, v26 offset:16896
	s_or_b64 exec, exec, s[62:63]
	v_cvt_pk_bf16_f32 v16, v16, v17
	v_cvt_pk_bf16_f32 v17, v20, v21
	v_add3_u32 v20, v24, v127, v133
	v_cvt_pk_bf16_f32 v18, v18, v19
	v_cvt_pk_bf16_f32 v19, v22, v23
	ds_write2st64_b64 v20, v[16:17], v[18:19] offset0:18 offset1:23
	ds_write_b64 v20, v[82:83] offset:14336

; __device__ __forceinline__ float b2f(u16 b) { return __uint_as_float(((unsigned)b) << 16); }
; __device__ __forceinline__ float sigmoidf_(float x) { return __builtin_amdgcn_rcpf(1.f + __builtin_amdgcn_exp2f(-1.4426950408889634f * x)); }
; __device__ __forceinline__ void scan_pc(const Params& p, int j, const u16* R, const u16* K, const u16* V, u16* Y, u16* YB) {
;     ...
;     auto load_raw = [&](int c, Raw& q_) {
;       unsigned offA = (unsigned)(offA0 + c * dA);
;       _Pragma("unroll") for (int ks = 0; ks < 2; ++ks) { q_.rw[ks] = ldo<bf16x8>(wmid, offA + ks * 64); q_.ra[ks] = ldo<bf16x8>(amid, offA + ks * 64); }
;       _Pragma("unroll") for (int jj = 0; jj < 4; ++jj) {
;         unsigned off = (unsigned)(offK0[jj] + c * dK);
;         q_.rk[jj] = ldo<u16>(K, off); q_.rr[jj] = ldo<u16>(R, off); q_.rv[jj] = ldo<u16>(V, off);
;       }
;     };
;     auto load_yold = [&](int c) {
;       _Pragma("unroll") for (int jj = 0; jj < 4; ++jj) yo[jj] = b2f(ldo<u16>(Yw, (unsigned)(offK0[jj] + c * dK)));
;     };
;     auto stage_a = [&](int c, const Raw& q_) {
;       u16* IMG = shm + (c % 3) * IMG_ELEMS;
;       f32x4 cw = {0.f, 0.f, 0.f, 0.f}, ca = {0.f, 0.f, 0.f, 0.f};
;       _Pragma("unroll") for (int ks = 0; ks < 2; ++ks) { cw = MFMA16(q_.rw[ks], LB[ks * 64], cw); ca = MFMA16(q_.ra[ks], LB[(2 + ks) * 64], ca); }
;       float kv[4], kk[4], ic[4], lw[4];
;       _Pragma("unroll") for (int jj = 0; jj < 4; ++jj) {
;         kv[jj] = b2f(q_.rk[jj]);
;         kk[jj] = kv[jj] * kkme;
;         float ss = row_sum(kk[jj] * kk[jj]);
;         reinterpret_cast<float*>(IMG + IMG_PL)[128 + w4 * 16 + fq * 4 + jj] = ss;
;         lw[jj] = -0.8750360036f * sigmoidf_(w0c + cw[jj]);
;         ic[jj] = sigmoidf_(a0c + ca[jj]);
;       }
;       s4 lhi = pack4(lw[0], lw[1], lw[2], lw[3]);
;       s4 llo = pack4(lw[0] - b2f((u16)lhi[0]), lw[1] - b2f((u16)lhi[1]), lw[2] - b2f((u16)lhi[2]), lw[3] - b2f((u16)lhi[3]));
;       f32x4 cum = {0.f, 0.f, 0.f, 0.f};
;       cum = MFMA4(ltri, lhi, cum);
;       cum = MFMA4(ltri, llo, cum);
;       float bt[4], kt[4], ep3 = 0.f;
;       _Pragma("unroll") for (int jj = 0; jj < 4; ++jj) {
;         float ep = __builtin_amdgcn_exp2f(cum[jj]), em = __builtin_amdgcn_exp2f(-cum[jj]), ex = __builtin_amdgcn_exp2f(cum[jj] - lw[jj]);
;     ...
;         if (c + 2 < nch) stage_a(c + 2, rn);
;         load_raw(min(c + 4, nch - 1), rn);
.LBB0_2764:
	s_andn2_saveexec_b64 s[26:27], s[26:27]
	s_cbranch_execz .LBB0_2719
	s_waitcnt vmcnt(16)
	v_lshl_or_b32 v165, v219, 16, v218
	v_lshl_or_b32 v163, v221, 16, v220
	v_lshl_or_b32 v164, v223, 16, v222
	v_lshl_or_b32 v162, v225, 16, v224
	v_lshl_or_b32 v84, v227, 16, v226
	v_lshl_or_b32 v85, v229, 16, v228
	v_add_u32_e32 v50, 5, v90
	v_min_i32_e32 v50, s29, v50
	v_mul_lo_u32 v50, v50, s8
	v_add_u32_e32 v51, v50, v154
	v_add_u32_e32 v54, v50, v155
	v_add_u32_e32 v55, v50, v156
	v_add_u32_e32 v50, v50, v157
	global_load_ushort v220, v55, s[58:59]
	global_load_ushort v221, v50, s[58:59]
	global_load_ushort v218, v51, s[58:59]
	global_load_ushort v222, v51, s[54:55]
	global_load_ushort v219, v54, s[58:59]
	global_load_ushort v223, v54, s[54:55]
	global_load_ushort v224, v55, s[54:55]
	global_load_ushort v228, v55, s[4:5]
	global_load_ushort v227, v54, s[4:5]
	global_load_ushort v226, v51, s[4:5]
	global_load_ushort v225, v50, s[54:55]
	global_load_ushort v229, v50, s[4:5]
	v_add_u32_e32 v50, 3, v90
	v_cmp_gt_u32_e32 vcc, s2, v50
	s_and_saveexec_b64 s[30:31], vcc
	s_cbranch_execz .LBB0_2718
	s_mul_hi_u32 s62, s65, 0xaaaaaaab
	s_lshr_b32 s62, s62, 1
	s_mul_i32 s62, s62, 3
	v_subrev_u32_e32 v50, s62, v90
	s_waitcnt lgkmcnt(3)
	v_mfma_f32_16x16x32_bf16 v[8:11], v[8:11], v[230:233], 0
	s_mov_b32 s62, 0xbf60025c
	v_add_u32_e32 v50, 3, v50
	s_waitcnt lgkmcnt(2)
	v_mfma_f32_16x16x32_bf16 v[12:15], v[12:15], v[234:237], 0
	s_waitcnt lgkmcnt(1)
	v_mfma_f32_16x16x32_bf16 v[0:3], v[0:3], v[238:241], v[8:11]
	s_waitcnt lgkmcnt(0)
	v_mfma_f32_16x16x32_bf16 v[4:7], v[4:7], v[242:245], v[12:15]
	s_nop 5
	v_add_f32_e32 v0, v152, v0
	v_add_f32_e32 v1, v152, v1
	v_mul_f32_e32 v0, 0xbfb8aa3b, v0
	s_nop 2
	v_add_f32_e32 v4, v153, v4
	v_mul_f32_e32 v4, 0xbfb8aa3b, v4
	v_exp_f32_e32 v4, v4
	v_mul_f32_e32 v1, 0xbfb8aa3b, v1
	v_add_f32_e32 v2, v152, v2
	v_add_f32_e32 v3, v152, v3
	v_add_f32_e32 v4, 1.0, v4
	v_rcp_f32_e32 v10, v4
	v_add_f32_e32 v4, v153, v5
	v_mul_f32_e32 v4, 0xbfb8aa3b, v4
	v_exp_f32_e32 v4, v4
	v_exp_f32_e32 v0, v0
	v_exp_f32_e32 v1, v1
	v_mul_f32_e32 v2, 0xbfb8aa3b, v2
	v_add_f32_e32 v4, 1.0, v4
	v_rcp_f32_e32 v11, v4
	v_add_f32_e32 v4, v153, v6
	v_mul_f32_e32 v4, 0xbfb8aa3b, v4
	v_exp_f32_e32 v4, v4
	v_mul_f32_e32 v3, 0xbfb8aa3b, v3
	v_exp_f32_e32 v2, v2
	v_exp_f32_e32 v3, v3
	v_add_f32_e32 v4, 1.0, v4
	v_rcp_f32_e32 v6, v4
	v_add_f32_e32 v4, v153, v7
	v_add_f32_e32 v0, 1.0, v0
	v_add_f32_e32 v1, 1.0, v1
	v_mul_f32_e32 v4, 0xbfb8aa3b, v4
	v_rcp_f32_e32 v0, v0
	v_rcp_f32_e32 v1, v1
	v_add_f32_e32 v2, 1.0, v2
	v_add_f32_e32 v3, 1.0, v3
	v_exp_f32_e32 v4, v4
	v_rcp_f32_e32 v2, v2
	v_rcp_f32_e32 v3, v3
	v_pk_mul_f32 v[12:13], v[0:1], s[62:63] op_sel_hi:[1,0]
	v_add_f32_e32 v4, 1.0, v4
	v_rcp_f32_e32 v7, v4
	v_pk_mul_f32 v[14:15], v[2:3], s[62:63] op_sel_hi:[1,0]
	v_cvt_pk_bf16_f32 v4, v12, v13
	v_mad_u32_u24 v8, v50, s80, 0
	v_cvt_pk_bf16_f32 v5, v14, v15
	v_and_b32_e32 v51, 0xffff0000, v4
	v_lshlrev_b32_e32 v50, 16, v4
	v_pk_fma_f32 v[0:1], v[0:1], s[62:63], v[50:51] op_sel_hi:[1,0,1] neg_lo:[0,0,1] neg_hi:[0,0,1]
	v_and_b32_e32 v51, 0xffff0000, v5
	v_lshlrev_b32_e32 v50, 16, v5
	v_pk_fma_f32 v[2:3], v[2:3], s[62:63], v[50:51] op_sel_hi:[1,0,1] neg_lo:[0,0,1] neg_hi:[0,0,1]
	v_cvt_pk_bf16_f32 v50, v0, v1
	v_cvt_pk_bf16_f32 v51, v2, v3
	v_mfma_f32_16x16x16_bf16 v[0:3], v[72:73], v[4:5], 0
	v_add_u32_e32 v60, v8, v115
	v_add_u32_e32 v61, v60, v117
	v_add3_u32 v66, v8, v117, v115
	v_mfma_f32_16x16x16_bf16 v[2:5], v[72:73], v[50:51], v[0:3]
	v_add_u32_e32 v9, v8, v113
	v_add_u32_e32 v62, v9, v112
	v_lshl_add_u32 v63, v97, 2, v9
	s_nop 4
	v_sub_f32_e32 v0, v2, v12
	v_exp_f32_e32 v58, v2
	v_exp_f32_e64 v50, -v2
	v_exp_f32_e32 v59, v0
	v_exp_f32_e32 v67, v3
	v_exp_f32_e64 v51, -v3
	v_sub_f32_e32 v0, v3, v13
	v_and_b32_e32 v3, 0xffff0000, v165
	v_lshlrev_b32_e32 v2, 16, v165
	v_pk_mul_f32 v[54:55], v[76:77], v[2:3]
	v_exp_f32_e32 v68, v0
	v_pk_mul_f32 v[0:1], v[54:55], v[54:55]
	s_nop 1
	v_mov_b32_dpp v0, v0 quad_perm:[1,0,3,2] row_mask:0xf bank_mask:0xf bound_ctrl:1
	v_mov_b32_dpp v1, v1 quad_perm:[1,0,3,2] row_mask:0xf bank_mask:0xf bound_ctrl:1
	v_pk_fma_f32 v[0:1], v[54:55], v[54:55], v[0:1]
	s_nop 1
	v_mov_b32_dpp v12, v0 quad_perm:[2,3,0,1] row_mask:0xf bank_mask:0xf bound_ctrl:1
	v_mov_b32_dpp v13, v1 quad_perm:[2,3,0,1] row_mask:0xf bank_mask:0xf bound_ctrl:1
	v_pk_add_f32 v[0:1], v[0:1], v[12:13]
	s_nop 1
	v_mov_b32_dpp v12, v0 row_half_mirror row_mask:0xf bank_mask:0xf bound_ctrl:1
	v_mov_b32_dpp v13, v1 row_half_mirror row_mask:0xf bank_mask:0xf bound_ctrl:1
	v_pk_add_f32 v[0:1], v[0:1], v[12:13]
	s_nop 1
	v_mov_b32_dpp v12, v0 row_ror:8 row_mask:0xf bank_mask:0xf bound_ctrl:1
	v_mov_b32_dpp v13, v1 row_ror:8 row_mask:0xf bank_mask:0xf bound_ctrl:1
	v_pk_add_f32 v[12:13], v[0:1], v[12:13]
	v_mul_f32_e64 v0, v59, -v54
	v_cvt_pk_bf16_f32 v0, v0, s0
	ds_write_b16 v61, v0
	v_pk_mul_f32 v[0:1], v[54:55], v[10:11]
	v_pk_add_f32 v[10:11], v[10:11], -1.0 op_sel_hi:[1,0]
	v_pk_mul_f32 v[0:1], v[0:1], v[50:51]
	v_pk_fma_f32 v[10:11], v[74:75], v[10:11], 1.0 op_sel_hi:[1,1,0]
; __device__ __forceinline__ float b2f(u16 b) { return __uint_as_float(((unsigned)b) << 16); }
; __device__ __forceinline__ void scan_pc(const Params& p, int j, const u16* R, const u16* K, const u16* V, u16* Y, u16* YB) {
;     ...
;       _Pragma("unroll") for (int jj = 0; jj < 4; ++jj) {
;         float ep = __builtin_amdgcn_exp2f(cum[jj]), em = __builtin_amdgcn_exp2f(-cum[jj]), ex = __builtin_amdgcn_exp2f(cum[jj] - lw[jj]);
;         float at = -kk[jj] * ex;
;         float rraw = b2f(q_.rr[jj]);
;         float rt = rraw * ep;
;         float kd = kv[jj] * (1.f + (ic[jj] - 1.f) * kac);
;         bt[jj] = kk[jj] * ic[jj] * em;
;         kt[jj] = kd * em;
;         int t = fq * 4 + jj, kc = w4 * 16 + fr;
;         float bsum = row_sum(rraw * kd * rkc);
;         reinterpret_cast<float*>(IMG + IMG_PL)[64 + w4 * 16 + t] = bsum;
;         IMG[(0 * 16 + t) * XT_LD + kc] = f2b(at);
;         IMG[(1 * 16 + t) * XT_LD + kc] = f2b(rt);
;         IMG[(2 * 16 + t) * XT_LD + kc] = f2b(bt[jj]);
;         IMG[(3 * 16 + t) * XT_LD + kc] = f2b(kt[jj]);
;         if (jj == 3) ep3 = ep;
;       }
;       if (fq == 3) reinterpret_cast<float*>(IMG + IMG_PL)[w4 * 16 + fr] = ep3;
;       *reinterpret_cast<s4*>(IMG + IMG_XK + (0 * 64 + w4 * 16 + fr) * XK_LD + fq * 4) = pack4(bt[0], bt[1], bt[2], bt[3]);
;       *reinterpret_cast<s4*>(IMG + IMG_XK + (1 * 64 + w4 * 16 + fr) * XK_LD + fq * 4) = pack4(kt[0], kt[1], kt[2], kt[3]);
;       s4 vp; _Pragma("unroll") for (int jj = 0; jj < 4; ++jj) vp[jj] = (short)q_.rv[jj];
;       *reinterpret_cast<s4*>(IMG + IMG_VT + (w4 * 16 + fr) * XK_LD + fq * 4) = vp;
;     };
	v_cvt_pk_bf16_f32 v54, v0, s0
	v_pk_mul_f32 v[10:11], v[10:11], v[2:3]
	ds_write_b16 v66, v54 offset:4608
	v_pk_mul_f32 v[2:3], v[10:11], v[50:51]
	v_mul_f32_e64 v54, v68, -v55
	v_cvt_pk_bf16_f32 v50, v2, s0
	ds_write_b16 v66, v50 offset:6912
	v_lshlrev_b32_e32 v50, 16, v164
	v_and_b32_e32 v51, 0xffff0000, v164
	v_mul_f32_e32 v55, v58, v50
	v_cvt_pk_bf16_f32 v55, v55, s0
	v_pk_mul_f32 v[10:11], v[10:11], v[50:51]
	ds_write_b16 v66, v55 offset:2304
	v_mul_f32_e32 v55, v67, v51
	v_pk_mul_f32 v[50:51], v[78:79], v[10:11]
	v_exp_f32_e32 v66, v4
	s_nop 0
	v_mov_b32_dpp v50, v50 quad_perm:[1,0,3,2] row_mask:0xf bank_mask:0xf bound_ctrl:1
	v_mov_b32_dpp v51, v51 quad_perm:[1,0,3,2] row_mask:0xf bank_mask:0xf bound_ctrl:1
	v_pk_fma_f32 v[10:11], v[78:79], v[10:11], v[50:51]
	s_nop 1
	v_mov_b32_dpp v50, v10 quad_perm:[2,3,0,1] row_mask:0xf bank_mask:0xf bound_ctrl:1
	v_mov_b32_dpp v51, v11 quad_perm:[2,3,0,1] row_mask:0xf bank_mask:0xf bound_ctrl:1
	v_pk_add_f32 v[10:11], v[10:11], v[50:51]
	s_nop 1
	v_mov_b32_dpp v50, v10 row_half_mirror row_mask:0xf bank_mask:0xf bound_ctrl:1
	v_mov_b32_dpp v51, v11 row_half_mirror row_mask:0xf bank_mask:0xf bound_ctrl:1
	v_pk_add_f32 v[10:11], v[10:11], v[50:51]
	s_nop 1
	v_mov_b32_dpp v50, v10 row_ror:8 row_mask:0xf bank_mask:0xf bound_ctrl:1
	v_mov_b32_dpp v51, v11 row_ror:8 row_mask:0xf bank_mask:0xf bound_ctrl:1
	v_pk_add_f32 v[58:59], v[10:11], v[50:51]
	v_cvt_pk_bf16_f32 v10, v54, s0
	v_add_u32_e32 v11, v60, v120
	ds_write_b16 v11, v10
	v_cvt_pk_bf16_f32 v10, v55, s0
	v_add3_u32 v11, v8, v120, v115
	ds_write_b16 v11, v10 offset:2304
	v_cvt_pk_bf16_f32 v10, v1, s0
	v_exp_f32_e64 v50, -v4
	v_sub_f32_e32 v4, v4, v14
	v_and_b32_e32 v55, 0xffff0000, v163
	v_lshlrev_b32_e32 v54, 16, v163
	ds_write_b16 v11, v10 offset:4608
	v_cvt_pk_bf16_f32 v10, v3, s0
	v_exp_f32_e32 v67, v4
	v_sub_f32_e32 v4, v5, v15
	v_pk_mul_f32 v[60:61], v[76:77], v[54:55]
	ds_write_b16 v11, v10 offset:6912
	v_exp_f32_e32 v10, v5
	v_exp_f32_e64 v51, -v5
	v_exp_f32_e32 v68, v4
	v_pk_mul_f32 v[4:5], v[60:61], v[60:61]
	s_nop 1
	v_mov_b32_dpp v4, v4 quad_perm:[1,0,3,2] row_mask:0xf bank_mask:0xf bound_ctrl:1
	v_mov_b32_dpp v5, v5 quad_perm:[1,0,3,2] row_mask:0xf bank_mask:0xf bound_ctrl:1
	v_pk_fma_f32 v[4:5], v[60:61], v[60:61], v[4:5]
	s_nop 1
	v_mov_b32_dpp v14, v4 quad_perm:[2,3,0,1] row_mask:0xf bank_mask:0xf bound_ctrl:1
	v_mov_b32_dpp v15, v5 quad_perm:[2,3,0,1] row_mask:0xf bank_mask:0xf bound_ctrl:1
	v_pk_add_f32 v[4:5], v[4:5], v[14:15]
	s_nop 1
	v_mov_b32_dpp v14, v4 row_half_mirror row_mask:0xf bank_mask:0xf bound_ctrl:1
	v_mov_b32_dpp v15, v5 row_half_mirror row_mask:0xf bank_mask:0xf bound_ctrl:1
	v_pk_add_f32 v[4:5], v[4:5], v[14:15]
	s_nop 1
	v_mov_b32_dpp v14, v4 row_ror:8 row_mask:0xf bank_mask:0xf bound_ctrl:1
	v_mov_b32_dpp v15, v5 row_ror:8 row_mask:0xf bank_mask:0xf bound_ctrl:1
	v_pk_add_f32 v[14:15], v[4:5], v[14:15]
	v_mul_f32_e64 v4, v67, -v60
	v_cvt_pk_bf16_f32 v4, v4, s0
	ds_write_b16 v11, v4 offset:144
	v_pk_mul_f32 v[4:5], v[60:61], v[6:7]
	v_pk_add_f32 v[6:7], v[6:7], -1.0 op_sel_hi:[1,0]
	v_pk_mul_f32 v[4:5], v[4:5], v[50:51]
	ds_write_b128 v62, v[12:15] offset:17408
	v_cvt_pk_bf16_f32 v12, v4, s0
	v_pk_fma_f32 v[6:7], v[74:75], v[6:7], 1.0 op_sel_hi:[1,1,0]
	ds_write_b16 v11, v12 offset:4752
	v_pk_mul_f32 v[12:13], v[6:7], v[54:55]
	v_and_b32_e32 v15, 0xffff0000, v162
	v_pk_mul_f32 v[6:7], v[12:13], v[50:51]
	v_mul_f32_e64 v62, v68, -v61
	v_cvt_pk_bf16_f32 v14, v6, s0
	ds_write_b16 v11, v14 offset:7056
	v_lshlrev_b32_e32 v14, 16, v162
	v_mul_f32_e32 v50, v66, v14
	v_cvt_pk_bf16_f32 v50, v50, s0
	v_pk_mul_f32 v[12:13], v[12:13], v[14:15]
	ds_write_b16 v11, v50 offset:2448
	v_mul_f32_e32 v50, v10, v15
	v_pk_mul_f32 v[14:15], v[78:79], v[12:13]
	s_nop 1
	v_mov_b32_dpp v14, v14 quad_perm:[1,0,3,2] row_mask:0xf bank_mask:0xf bound_ctrl:1
	v_mov_b32_dpp v15, v15 quad_perm:[1,0,3,2] row_mask:0xf bank_mask:0xf bound_ctrl:1
	v_pk_fma_f32 v[12:13], v[78:79], v[12:13], v[14:15]
	s_nop 1
	v_mov_b32_dpp v14, v12 quad_perm:[2,3,0,1] row_mask:0xf bank_mask:0xf bound_ctrl:1
	v_mov_b32_dpp v15, v13 quad_perm:[2,3,0,1] row_mask:0xf bank_mask:0xf bound_ctrl:1
	v_pk_add_f32 v[12:13], v[12:13], v[14:15]
	s_nop 1
	v_mov_b32_dpp v14, v12 row_half_mirror row_mask:0xf bank_mask:0xf bound_ctrl:1
	v_mov_b32_dpp v15, v13 row_half_mirror row_mask:0xf bank_mask:0xf bound_ctrl:1
	v_pk_add_f32 v[12:13], v[12:13], v[14:15]
	s_nop 1
	v_mov_b32_dpp v14, v12 row_ror:8 row_mask:0xf bank_mask:0xf bound_ctrl:1
	v_mov_b32_dpp v15, v13 row_ror:8 row_mask:0xf bank_mask:0xf bound_ctrl:1
	v_pk_add_f32 v[60:61], v[12:13], v[14:15]
	v_cvt_pk_bf16_f32 v12, v62, s0
	ds_write_b16 v11, v12 offset:288
	v_cvt_pk_bf16_f32 v12, v50, s0
	ds_write_b16 v11, v12 offset:2592
	v_cvt_pk_bf16_f32 v12, v5, s0
	ds_write_b16 v11, v12 offset:4896
	v_cvt_pk_bf16_f32 v12, v7, s0
	ds_write_b128 v63, v[58:61] offset:17152
	ds_write_b16 v11, v12 offset:7200
	s_and_saveexec_b64 s[62:63], s[12:13]
	s_cbranch_execz .LBB0_2717
	v_lshl_add_u32 v9, v96, 2, v9
	ds_write_b32 v9, v10 offset:16896
	s_branch .LBB0_2717
